# wave reductions of the layer-0 modulate phase and the readout phase via DPP operands / permlane swaps (no ds_bpermute round trips), on top of the scan-phase version
# speedup vs baseline: 1.0034x; 1.0034x over previous
; DI void row_normalize(float (&v)[32]) {
;     float s = 0.f;
; #pragma unroll
;     for (int i = 0; i < 32; ++i) s += v[i];
;     const float mean = wave_sum(s) * (1.0f / D);
;     float q = 0.f;
; #pragma unroll
;     for (int i = 0; i < 32; ++i) { v[i] -= mean; q += v[i] * v[i]; }
;     const float rstd = rsqrtf(wave_sum(q) * (1.0f / D) + LN_EPS);
; DI void phase_modulate1(int l, int wv) {
;     ...
;         load_row_f32(xrow(xin, cin, F.X, l, r), F.lane, v);
;         load_row_f32(md + 0 * D, F.lane, sh); load_row_f32(md + 1 * D, F.lane, sc);
;         row_normalize(v);
; #pragma unroll
;         for (int i = 0; i < 32; ++i) v[i] = v[i] * (1.0f + sc[i]) + sh[i];
.LBB0_174:
	s_cmpk_lt_i32 s8, 0x4000
	s_cselect_b32 s26, s16, s18
	s_cselect_b32 s27, s17, s19
	s_add_i32 s22, s8, 0xffffc000
	s_cmpk_lt_i32 s8, 0x4000
	s_cselect_b32 s23, s9, 0
	s_cselect_b32 s22, s8, s22
	s_ashr_i32 s24, s8, 31
	s_lshr_b32 s24, s24, 21
	s_add_i32 s24, s8, s24
	s_ashr_i32 s24, s24, 11
	s_cmpk_lt_i32 s8, 0x4000
	v_lshl_add_u64 v[0:1], s[6:7], 0, v[34:35]
	s_cselect_b32 s24, s24, 8
	v_add_co_u32_e32 v48, vcc, s31, v0
	s_mul_hi_i32 s25, s24, 0xc000
	s_mul_i32 s24, s24, 0xc000
	v_lshl_add_u64 v[2:3], s[6:7], 0, v[32:33]
	v_addc_co_u32_e32 v49, vcc, 0, v1, vcc
	s_add_u32 s24, s20, s24
	v_add_co_u32_e32 v46, vcc, s28, v2
	s_addc_u32 s25, s21, s25
	s_nop 0
	v_addc_co_u32_e32 v47, vcc, 0, v3, vcc
	v_lshl_add_u64 v[26:27], s[24:25], 0, v[36:37]
	s_movk_i32 s24, 0x2000
	v_add_co_u32_e32 v28, vcc, s24, v26
	s_lshl_b64 s[22:23], s[22:23], 13
	s_nop 0
	v_addc_co_u32_e32 v29, vcc, 0, v27, vcc
	s_add_u32 s22, s27, s22
	v_add_co_u32_e32 v4, vcc, s29, v26
	s_addc_u32 s23, s26, s23
	s_mov_b64 s[24:25], 0x3000
	v_addc_co_u32_e32 v5, vcc, 0, v27, vcc
	v_lshl_add_u64 v[0:1], v[26:27], 0, s[38:39]
	v_lshl_add_u64 v[2:3], v[26:27], 0, s[24:25]
	v_lshl_add_u64 v[6:7], v[26:27], 0, s[40:41]
	global_load_dwordx4 v[56:59], v[28:29], off
	global_load_dwordx4 v[60:63], v[0:1], off offset:16
	global_load_dwordx4 v[64:67], v[0:1], off offset:2048
	global_load_dwordx4 v[68:71], v[0:1], off offset:2064
	global_load_dwordx4 v[72:75], v[4:5], off
	global_load_dwordx4 v[76:79], v[2:3], off offset:16
	global_load_dwordx4 v[80:83], v[4:5], off offset:2048
	global_load_dwordx4 v[88:91], v[6:7], off offset:16
	v_lshl_add_u64 v[4:5], s[22:23], 0, v[36:37]
	global_load_dwordx4 v[94:97], v[4:5], off
	global_load_dwordx4 v[6:9], v[4:5], off offset:16
	global_load_dwordx4 v[0:3], v[4:5], off offset:2048
	global_load_dwordx4 v[10:13], v[4:5], off offset:2064
	v_add_co_u32_e32 v16, vcc, s61, v4
	v_lshl_add_u64 v[14:15], v[4:5], 0, s[34:35]
	s_nop 0
	v_addc_co_u32_e32 v17, vcc, 0, v5, vcc
	v_lshl_add_u64 v[4:5], v[4:5], 0, s[36:37]
	global_load_dwordx4 v[22:25], v[16:17], off
	global_load_dwordx4 v[18:21], v[14:15], off offset:16
	s_nop 0
	global_load_dwordx4 v[14:17], v[16:17], off offset:2048
	s_nop 0
	global_load_dwordx4 v[112:115], v[4:5], off offset:16
	v_lshl_add_u64 v[130:131], v[26:27], 0, s[36:37]
	v_mov_b32_e32 v38, v129
	v_mov_b32_e32 v39, v129
	v_mov_b32_e32 v40, v129
	v_mov_b32_e32 v41, v129
	v_mov_b32_e32 v42, v129
	v_mov_b32_e32 v43, v129
	v_mov_b32_e32 v44, v129
	v_mov_b32_e32 v45, v129
	s_add_u32 s8, s8, s10
	s_addc_u32 s9, s9, s11
	v_lshl_add_u64 v[32:33], v[32:33], 0, s[12:13]
	v_lshl_add_u64 v[34:35], v[34:35], 0, s[14:15]
	s_cmpk_lt_i32 s8, 0x4800
	s_waitcnt vmcnt(15)
	v_add_f32_e32 v87, 1.0, v58
	s_waitcnt vmcnt(14)
	v_add_f32_e32 v58, 1.0, v61
	s_waitcnt vmcnt(13)
	v_add_f32_e32 v61, 1.0, v64
	v_add_f32_e32 v64, 1.0, v67
	s_waitcnt vmcnt(12)
	v_add_f32_e32 v67, 1.0, v70
	s_waitcnt vmcnt(11)
	v_add_f32_e32 v70, 1.0, v73
	s_waitcnt vmcnt(7)
	v_add_f32_e32 v4, 0, v94
	v_add_f32_e32 v4, v95, v4
	v_add_f32_e32 v4, v96, v4
	v_add_f32_e32 v4, v97, v4
	s_waitcnt vmcnt(6)
	v_add_f32_e32 v4, v6, v4
	v_add_f32_e32 v4, v7, v4
	v_add_f32_e32 v4, v8, v4
	v_add_f32_e32 v4, v9, v4
	s_waitcnt vmcnt(5)
	v_add_f32_e32 v4, v0, v4
	v_add_f32_e32 v4, v1, v4
	v_add_f32_e32 v4, v2, v4
	v_add_f32_e32 v4, v3, v4
	s_waitcnt vmcnt(4)
	v_add_f32_e32 v4, v10, v4
	v_add_f32_e32 v4, v11, v4
	v_add_f32_e32 v4, v12, v4
	v_add_f32_e32 v4, v13, v4
	s_waitcnt vmcnt(3)
	v_add_f32_e32 v4, v22, v4
	v_add_f32_e32 v4, v23, v4
	v_add_f32_e32 v4, v24, v4
	v_add_f32_e32 v4, v25, v4
	s_waitcnt vmcnt(2)
	v_add_f32_e32 v4, v18, v4
	v_add_f32_e32 v4, v19, v4
	v_add_f32_e32 v4, v20, v4
	v_add_f32_e32 v4, v21, v4
	s_waitcnt vmcnt(1)
	v_add_f32_e32 v4, v14, v4
	v_add_f32_e32 v4, v15, v4
	v_add_f32_e32 v4, v16, v4
	v_add_f32_e32 v4, v17, v4
	s_waitcnt vmcnt(0)
	v_add_f32_e32 v4, v112, v4
	v_add_f32_e32 v4, v113, v4
	v_add_f32_e32 v4, v114, v4
	v_add_f32_e32 v4, v115, v4
	v_add_f32_e32 v73, 1.0, v76
	v_add_f32_e32 v76, 1.0, v79
	v_add_f32_e32 v79, 1.0, v82
	v_add_f32_e32 v82, 1.0, v89
	s_waitcnt lgkmcnt(0)
	s_nop 1
	v_add_f32_dpp v4, v4, v4 quad_perm:[1,0,3,2] row_mask:0xf bank_mask:0xf bound_ctrl:1
	v_add_f32_e32 v92, 1.0, v56
	v_add_f32_e32 v56, 1.0, v59
	v_add_f32_e32 v59, 1.0, v62
	v_add_f32_e32 v62, 1.0, v65
	s_waitcnt lgkmcnt(0)
	s_nop 1
	v_add_f32_dpp v4, v4, v4 quad_perm:[2,3,0,1] row_mask:0xf bank_mask:0xf bound_ctrl:1
	v_add_f32_e32 v65, 1.0, v68
	v_add_f32_e32 v68, 1.0, v71
	v_add_f32_e32 v71, 1.0, v74
	v_add_f32_e32 v74, 1.0, v77
	s_waitcnt lgkmcnt(0)
	s_nop 1
	v_add_f32_dpp v4, v4, v4 row_half_mirror row_mask:0xf bank_mask:0xf bound_ctrl:1
	v_add_f32_e32 v77, 1.0, v80
	v_add_f32_e32 v80, 1.0, v83
	v_add_f32_e32 v83, 1.0, v90
	v_add_f32_e32 v84, 1.0, v91
	s_waitcnt lgkmcnt(0)
	s_nop 1
	v_add_f32_dpp v4, v4, v4 row_mirror row_mask:0xf bank_mask:0xf bound_ctrl:1
	v_add_f32_e32 v86, 1.0, v57
	v_add_f32_e32 v57, 1.0, v60
	v_add_f32_e32 v60, 1.0, v63
	v_add_f32_e32 v63, 1.0, v66
	s_waitcnt lgkmcnt(0)
	v_mov_b32_e32 v5, v4
	s_nop 1
	v_permlane16_swap_b32_e32 v4, v5
	s_nop 1
	v_add_f32_e32 v4, v4, v5
	v_add_f32_e32 v66, 1.0, v69
	v_add_f32_e32 v69, 1.0, v72
	v_add_f32_e32 v72, 1.0, v75
	v_add_f32_e32 v75, 1.0, v78
	s_waitcnt lgkmcnt(0)
; DI const float* inp(int i) { return as_global<const float>(ld_ptr(i)); }
; DI void row_normalize(float (&v)[32]) {
;     ...
;     const float mean = wave_sum(s) * (1.0f / D);
;     float q = 0.f;
; #pragma unroll
;     for (int i = 0; i < 32; ++i) { v[i] -= mean; q += v[i] * v[i]; }
;     const float rstd = rsqrtf(wave_sum(q) * (1.0f / D) + LN_EPS);
; #pragma unroll
;     for (int i = 0; i < 32; ++i) v[i] *= rstd;
; }
; DI void phase_modulate1(int l, int wv) {
;     const Frame F = mkframe(wv);
;     const float* xin = inp(I_X); const float* cin = inp(I_CTX);
;     const int gw = blockIdx.x * NWAVES + F.wave, NGW = F.G * NWAVES;
;     for (int r = gw; r < NTOK; r += NGW) {
;         const float* md = F.mod + ((size_t)l * 9 + modrow(r)) * MODW;
;         float v[32], sh[32], sc[32];
;         load_row_f32(xrow(xin, cin, F.X, l, r), F.lane, v);
;         load_row_f32(md + 0 * D, F.lane, sh); load_row_f32(md + 1 * D, F.lane, sc);
;         row_normalize(v);
; #pragma unroll
;         for (int i = 0; i < 32; ++i) v[i] = v[i] * (1.0f + sc[i]) + sh[i];
	v_mov_b32_e32 v5, v4
	s_nop 1
	v_permlane32_swap_b32_e32 v4, v5
	s_nop 1
	v_add_f32_e32 v5, v4, v5
	v_mul_f32_e32 v4, 0x3a000000, v5
	v_fmamk_f32 v100, v5, 0xba000000, v95
	v_fmamk_f32 v99, v5, 0xba000000, v94
	v_fmamk_f32 v101, v5, 0xba000000, v96
	v_fmac_f32_e32 v97, 0xba000000, v5
	v_fmamk_f32 v102, v5, 0xba000000, v6
	v_fmamk_f32 v103, v5, 0xba000000, v7
	v_fmamk_f32 v104, v5, 0xba000000, v8
	v_fmac_f32_e32 v9, 0xba000000, v5
	v_fmamk_f32 v105, v5, 0xba000000, v0
	v_fmamk_f32 v106, v5, 0xba000000, v1
	v_fmamk_f32 v107, v5, 0xba000000, v2
	v_fmac_f32_e32 v3, 0xba000000, v5
	v_fmamk_f32 v108, v5, 0xba000000, v10
	v_fmamk_f32 v109, v5, 0xba000000, v11
	v_fmamk_f32 v110, v5, 0xba000000, v12
	v_fmac_f32_e32 v13, 0xba000000, v5
	v_fmamk_f32 v117, v5, 0xba000000, v22
	v_fmamk_f32 v118, v5, 0xba000000, v23
	v_fmamk_f32 v24, v5, 0xba000000, v24
	v_fmac_f32_e32 v25, 0xba000000, v5
	v_fmamk_f32 v119, v5, 0xba000000, v18
	v_fmamk_f32 v120, v5, 0xba000000, v19
	v_fmamk_f32 v121, v5, 0xba000000, v20
	v_fmac_f32_e32 v21, 0xba000000, v5
	v_fmamk_f32 v122, v5, 0xba000000, v14
	v_fmamk_f32 v123, v5, 0xba000000, v15
	v_fmamk_f32 v124, v5, 0xba000000, v16
	v_fmac_f32_e32 v17, 0xba000000, v5
	v_pk_add_f32 v[30:31], v[112:113], v[4:5] op_sel_hi:[1,0] neg_lo:[0,1] neg_hi:[0,1]
	v_pk_add_f32 v[22:23], v[114:115], v[4:5] op_sel_hi:[1,0] neg_lo:[0,1] neg_hi:[0,1]
	v_mul_f32_e32 v2, v100, v100
	global_load_dwordx4 v[4:7], v[26:27], off
	v_fmac_f32_e32 v2, v99, v99
	v_fmac_f32_e32 v2, v101, v101
	v_fmac_f32_e32 v2, v97, v97
	v_fmac_f32_e32 v2, v102, v102
	v_fmac_f32_e32 v2, v103, v103
	v_fmac_f32_e32 v2, v104, v104
	v_fmac_f32_e32 v2, v9, v9
	v_fmac_f32_e32 v2, v105, v105
	v_fmac_f32_e32 v2, v106, v106
	v_fmac_f32_e32 v2, v107, v107
	v_fmac_f32_e32 v2, v3, v3
	v_fmac_f32_e32 v2, v108, v108
	v_fmac_f32_e32 v2, v109, v109
	v_fmac_f32_e32 v2, v110, v110
	v_fmac_f32_e32 v2, v13, v13
	v_fmac_f32_e32 v2, v117, v117
	v_fmac_f32_e32 v2, v118, v118
	v_fmac_f32_e32 v2, v24, v24
	v_fmac_f32_e32 v2, v25, v25
	v_fmac_f32_e32 v2, v119, v119
	v_fmac_f32_e32 v2, v120, v120
	v_fmac_f32_e32 v2, v121, v121
	v_fmac_f32_e32 v2, v21, v21
	v_fmac_f32_e32 v2, v122, v122
	v_fmac_f32_e32 v2, v123, v123
	v_fmac_f32_e32 v2, v124, v124
	v_pk_mul_f32 v[0:1], v[30:31], v[30:31]
	v_fmac_f32_e32 v2, v17, v17
	v_add_f32_e32 v0, v0, v2
	v_add_f32_e32 v2, v1, v0
	v_pk_mul_f32 v[0:1], v[22:23], v[22:23]
	v_lshl_add_u64 v[112:113], v[26:27], 0, s[34:35]
	v_add_f32_e32 v0, v0, v2
	v_add_f32_e32 v0, v1, v0
	v_add_f32_e32 v78, 1.0, v81
	v_add_f32_e32 v81, 1.0, v88
	s_waitcnt lgkmcnt(0)
	s_nop 1
	v_add_f32_dpp v0, v0, v0 quad_perm:[1,0,3,2] row_mask:0xf bank_mask:0xf bound_ctrl:1
	s_waitcnt lgkmcnt(0)
	s_nop 1
	v_add_f32_dpp v0, v0, v0 quad_perm:[2,3,0,1] row_mask:0xf bank_mask:0xf bound_ctrl:1
	s_waitcnt lgkmcnt(0)
	s_nop 1
	v_add_f32_dpp v0, v0, v0 row_half_mirror row_mask:0xf bank_mask:0xf bound_ctrl:1
	s_waitcnt lgkmcnt(0)
	s_nop 1
	v_add_f32_dpp v0, v0, v0 row_mirror row_mask:0xf bank_mask:0xf bound_ctrl:1
	s_waitcnt lgkmcnt(0)
	v_mov_b32_e32 v1, v0
	s_nop 1
	v_permlane16_swap_b32_e32 v0, v1
	s_nop 1
	v_add_f32_e32 v0, v0, v1
	s_waitcnt lgkmcnt(0)
	v_mov_b32_e32 v1, v0
	s_nop 1
	v_permlane32_swap_b32_e32 v0, v1
	s_nop 1
	v_add_f32_e32 v0, v0, v1
	v_fmamk_f32 v0, v0, 0x3a000000, v206
	v_mul_f32_e32 v1, 0x4b800000, v0
	v_cmp_gt_f32_e32 vcc, s30, v0
	s_nop 1
	v_cndmask_b32_e32 v0, v0, v1, vcc
	v_rsq_f32_e32 v0, v0
	s_nop 0
	v_mul_f32_e32 v1, 0x45800000, v0
	v_cndmask_b32_e32 v125, v0, v1, vcc
	v_mul_f32_e32 v89, v9, v125
	global_load_dwordx4 v[8:11], v[26:27], off offset:16
	v_mul_f32_e32 v90, v3, v125
	global_load_dwordx4 v[0:3], v[26:27], off offset:2064
	v_mul_f32_e32 v91, v13, v125
	global_load_dwordx4 v[12:15], v[26:27], off offset:2048
	v_add_co_u32_e32 v126, vcc, s61, v26
	v_mul_f32_e32 v85, v97, v125
	v_mul_f32_e32 v88, v25, v125
	v_mul_f32_e32 v93, v21, v125
	v_addc_co_u32_e32 v127, vcc, 0, v27, vcc
	v_mul_f32_e32 v94, v17, v125
	global_load_dwordx4 v[16:19], v[28:29], off offset:-4096
	v_mul_f32_e32 v97, v22, v125
	v_mul_f32_e32 v98, v23, v125
	global_load_dwordx4 v[20:23], v[112:113], off offset:16
	v_mul_f32_e32 v25, v99, v125
	v_mul_f32_e32 v28, v100, v125
	v_mul_f32_e32 v29, v101, v125
	v_mul_f32_e32 v95, v30, v125
	v_mul_f32_e32 v96, v31, v125
	v_mul_f32_e32 v113, v107, v125
	v_mul_f32_e32 v107, v24, v125
	s_waitcnt vmcnt(5)
	v_fma_f32 v4, v92, v25, v4
	global_load_dwordx4 v[24:27], v[126:127], off offset:2048
	v_fma_f32 v5, v86, v28, v5
	v_fma_f32 v6, v87, v29, v6
	global_load_dwordx4 v[28:31], v[130:131], off offset:16
	v_mul_f32_e32 v114, v102, v125
	v_mul_f32_e32 v115, v103, v125
	v_mul_f32_e32 v111, v105, v125
	v_mul_f32_e32 v112, v106, v125
	v_mul_f32_e32 v108, v108, v125
	v_mul_f32_e32 v109, v109, v125
	v_mul_f32_e32 v105, v117, v125
	v_mul_f32_e32 v106, v118, v125
	v_mul_f32_e32 v102, v119, v125
	v_mul_f32_e32 v103, v120, v125
	v_fmac_f32_e32 v7, v56, v85
	v_cvt_pk_bf16_f32 v56, v4, v5
	v_mul_f32_e32 v4, 0x41800000, v4
	v_mul_f32_e32 v5, 0x41800000, v5
	v_mul_f32_e32 v99, v122, v125
	v_mul_f32_e32 v100, v123, v125
	v_med3_f32 v4, v4, s33, v238
	v_med3_f32 v5, v5, s33, v238
	v_mul_f32_e32 v116, v104, v125
	v_cvt_pk_fp8_f32 v38, v4, v5
	v_mul_f32_e32 v110, v110, v125
	v_mul_f32_e32 v104, v121, v125
	v_mul_f32_e32 v101, v124, v125
	s_waitcnt vmcnt(6)
; DI unsigned pk4_fp8(float a, float b, float c, float d) { int w = 0; w = __builtin_amdgcn_cvt_pk_fp8_f32(clamp448(a), clamp448(b), w, false); w = __builtin_amdgcn_cvt_pk_fp8_f32(clamp448(c), clamp448(d), w, true); return (unsigned)w; }
; DI void phase_modulate1(int l, int wv) {
;     ...
;         for (int i = 0; i < 32; ++i) v[i] = v[i] * (1.0f + sc[i]) + sh[i];
;         store_row_bf16(F.H + (size_t)r * D, F.lane, v);
;         unsigned char* h8 = F.ws + WS_H8 + (size_t)r * D;
; #pragma unroll
;         for (int c = 0; c < 4; ++c) *(u32x2*)(h8 + c * 512 + F.lane * 8) = (u32x2){pk4_fp8(v[c * 8 + 0] * SA8_H, v[c * 8 + 1] * SA8_H, v[c * 8 + 2] * SA8_H, v[c * 8 + 3] * SA8_H), pk4_fp8(v[c * 8 + 4] * SA8_H, v[c * 8 + 5] * SA8_H, v[c * 8 + 6] * SA8_H, v[c * 8 + 7] * SA8_H)};
	v_fma_f32 v8, v57, v114, v8
	v_fma_f32 v9, v58, v115, v9
	s_waitcnt vmcnt(5)
	v_fma_f32 v0, v65, v108, v0
	v_fma_f32 v1, v66, v109, v1
	s_waitcnt vmcnt(4)
	v_fma_f32 v12, v61, v111, v12
	v_fma_f32 v13, v62, v112, v13
	v_cvt_pk_bf16_f32 v58, v8, v9
	v_mul_f32_e32 v8, 0x41800000, v8
	v_mul_f32_e32 v9, 0x41800000, v9
	v_fmac_f32_e32 v11, v60, v89
	v_cvt_pk_bf16_f32 v60, v12, v13
	v_cvt_pk_bf16_f32 v62, v0, v1
	v_mul_f32_e32 v12, 0x41800000, v12
	s_waitcnt vmcnt(3)
	v_fma_f32 v16, v69, v105, v16
	v_fma_f32 v17, v70, v106, v17
	v_mul_f32_e32 v13, 0x41800000, v13
	s_waitcnt vmcnt(2)
	v_fma_f32 v20, v73, v102, v20
	v_fma_f32 v21, v74, v103, v21
	v_mul_f32_e32 v0, 0x41800000, v0
	v_mul_f32_e32 v1, 0x41800000, v1
	v_med3_f32 v8, v8, s33, v238
	v_med3_f32 v9, v9, s33, v238
	v_fmac_f32_e32 v15, v64, v90
	v_cvt_pk_bf16_f32 v64, v16, v17
	v_cvt_pk_bf16_f32 v66, v20, v21
	s_waitcnt vmcnt(1)
	v_fma_f32 v24, v77, v99, v24
	v_fma_f32 v25, v78, v100, v25
	v_mul_f32_e32 v16, 0x41800000, v16
	s_waitcnt vmcnt(0)
	v_fma_f32 v28, v81, v95, v28
	v_fma_f32 v29, v82, v96, v29
	v_mul_f32_e32 v17, 0x41800000, v17
	v_mul_f32_e32 v20, 0x41800000, v20
	v_mul_f32_e32 v21, 0x41800000, v21
	v_med3_f32 v12, v12, s33, v238
	v_med3_f32 v13, v13, s33, v238
	v_med3_f32 v0, v0, s33, v238
	v_med3_f32 v1, v1, s33, v238
	v_cvt_pk_fp8_f32 v39, v8, v9
	v_fma_f32 v10, v59, v116, v10
	v_fmac_f32_e32 v3, v68, v91
	v_cvt_pk_bf16_f32 v68, v24, v25
	v_cvt_pk_bf16_f32 v70, v28, v29
	v_mul_f32_e32 v24, 0x41800000, v24
	v_mul_f32_e32 v25, 0x41800000, v25
	v_mul_f32_e32 v28, 0x41800000, v28
	v_mul_f32_e32 v29, 0x41800000, v29
	v_med3_f32 v16, v16, s33, v238
	v_med3_f32 v17, v17, s33, v238
	v_med3_f32 v20, v20, s33, v238
	v_med3_f32 v21, v21, s33, v238
	v_cvt_pk_fp8_f32 v40, v12, v13
	v_cvt_pk_fp8_f32 v41, v0, v1
	v_fma_f32 v14, v63, v113, v14
	v_fma_f32 v2, v67, v110, v2
	v_cvt_pk_bf16_f32 v57, v6, v7
	v_cvt_pk_bf16_f32 v59, v10, v11
	v_mul_f32_e32 v6, 0x41800000, v6
	v_mul_f32_e32 v7, 0x41800000, v7
	v_mul_f32_e32 v10, 0x41800000, v10
	v_mul_f32_e32 v11, 0x41800000, v11
	v_med3_f32 v24, v24, s33, v238
	v_med3_f32 v25, v25, s33, v238
	v_med3_f32 v28, v28, s33, v238
	v_med3_f32 v29, v29, s33, v238
	v_cvt_pk_fp8_f32 v42, v16, v17
	v_cvt_pk_fp8_f32 v43, v20, v21
	v_fma_f32 v18, v71, v107, v18
	v_fmac_f32_e32 v19, v72, v88
	v_fma_f32 v22, v75, v104, v22
	v_fmac_f32_e32 v23, v76, v93
	v_cvt_pk_bf16_f32 v61, v14, v15
	v_cvt_pk_bf16_f32 v63, v2, v3
	v_mul_f32_e32 v14, 0x41800000, v14
	v_mul_f32_e32 v15, 0x41800000, v15
	v_mul_f32_e32 v2, 0x41800000, v2
	v_mul_f32_e32 v3, 0x41800000, v3
	v_med3_f32 v6, v6, s33, v238
	v_med3_f32 v7, v7, s33, v238
	v_med3_f32 v10, v10, s33, v238
	v_med3_f32 v11, v11, s33, v238
	v_cvt_pk_fp8_f32 v44, v24, v25
	v_cvt_pk_fp8_f32 v45, v28, v29
	v_fma_f32 v26, v79, v101, v26
	v_fmac_f32_e32 v27, v80, v94
	v_fma_f32 v30, v83, v97, v30
	v_fmac_f32_e32 v31, v84, v98
	v_cvt_pk_bf16_f32 v65, v18, v19
	v_cvt_pk_bf16_f32 v67, v22, v23
	v_mul_f32_e32 v18, 0x41800000, v18
	v_mul_f32_e32 v19, 0x41800000, v19
	v_mul_f32_e32 v22, 0x41800000, v22
	v_mul_f32_e32 v23, 0x41800000, v23
	v_med3_f32 v14, v14, s33, v238
	v_med3_f32 v15, v15, s33, v238
	v_med3_f32 v2, v2, s33, v238
	v_med3_f32 v3, v3, s33, v238
	v_cvt_pk_fp8_f32 v38, v6, v7 op_sel:[0,0,1]
	v_cvt_pk_fp8_f32 v39, v10, v11 op_sel:[0,0,1]
	v_cvt_pk_bf16_f32 v69, v26, v27
	v_cvt_pk_bf16_f32 v71, v30, v31
	v_mul_f32_e32 v26, 0x41800000, v26
	v_mul_f32_e32 v27, 0x41800000, v27
	v_mul_f32_e32 v30, 0x41800000, v30
	v_mul_f32_e32 v31, 0x41800000, v31
	v_med3_f32 v18, v18, s33, v238
	v_med3_f32 v19, v19, s33, v238
	v_med3_f32 v22, v22, s33, v238
	v_med3_f32 v23, v23, s33, v238
	v_cvt_pk_fp8_f32 v40, v14, v15 op_sel:[0,0,1]
	v_cvt_pk_fp8_f32 v41, v2, v3 op_sel:[0,0,1]
	v_med3_f32 v26, v26, s33, v238
	v_med3_f32 v27, v27, s33, v238
	v_med3_f32 v30, v30, s33, v238
	v_med3_f32 v31, v31, s33, v238
	v_cvt_pk_fp8_f32 v42, v18, v19 op_sel:[0,0,1]
	v_cvt_pk_fp8_f32 v43, v22, v23 op_sel:[0,0,1]
	v_cvt_pk_fp8_f32 v44, v26, v27 op_sel:[0,0,1]
	v_cvt_pk_fp8_f32 v45, v30, v31 op_sel:[0,0,1]
	global_store_dwordx4 v[48:49], v[56:59], off
	global_store_dwordx4 v[48:49], v[60:63], off offset:1024
	global_store_dwordx4 v[48:49], v[64:67], off offset:2048
	global_store_dwordx4 v[48:49], v[68:71], off offset:3072
	global_store_dwordx2 v[46:47], v[38:39], off
	global_store_dwordx2 v[46:47], v[40:41], off offset:512
	global_store_dwordx2 v[46:47], v[42:43], off offset:1024
	global_store_dwordx2 v[46:47], v[44:45], off offset:1536
	s_cbranch_scc1 .LBB0_174

; DI unsigned pk4_fp8(float a, float b, float c, float d) { int w = 0; w = __builtin_amdgcn_cvt_pk_fp8_f32(clamp448(a), clamp448(b), w, false); w = __builtin_amdgcn_cvt_pk_fp8_f32(clamp448(c), clamp448(d), w, true); return (unsigned)w; }
; DI void unpack8(const u32x4 w, float (&f)[8]) { f[0] = bf_lo(w.x); f[1] = bf_hi(w.x); f[2] = bf_lo(w.y); f[3] = bf_hi(w.y); f[4] = bf_lo(w.z); f[5] = bf_hi(w.z); f[6] = bf_lo(w.w); f[7] = bf_hi(w.w); }
; DI float silu(float x) { return x * frcp(1.0f + __expf(-x)); }
; DI void phase_readout(int l, int nrows, int wv) {
;     ...
;     auto row_compute = [&](int r, const RowIn& R) {
; #pragma unroll
;         for (int c = 0; c < 2; ++c) {
;             const int e0 = c * 512 + F.lane * 8;
;             float o[8], og[8], yb[8]; float ss = 0.f;
;             { float fa[8], fb[8]; unpack8(R.a[c], fa); unpack8(R.b[c], fb);
; #pragma unroll
;               for (int j = 0; j < 8; ++j) o[j] = fa[j] + fb[j]; }
; #pragma unroll
;             for (int j = 0; j < 8; ++j) ss += o[j] * o[j];
;             ss += __shfl_xor(ss, 1); ss += __shfl_xor(ss, 2); ss += __shfl_xor(ss, 4); ss += __shfl_xor(ss, 8);
;             const float rs = rsqrtf(ss * (1.0f / DK) + LN_EPS);
;             unpack8(R.og[c], og);
; #pragma unroll
;             for (int j = 0; j < 8; ++j) yb[j] = o[j] * rs * ng[(e0 + j) & (DK - 1)] * silu(og[j]);
;             *(u32x2*)((unsigned char*)F.H + (size_t)r * D + DC + e0) = (u32x2){pk4_fp8(yb[0] * SA8_Y, yb[1] * SA8_Y, yb[2] * SA8_Y, yb[3] * SA8_Y), pk4_fp8(yb[4] * SA8_Y, yb[5] * SA8_Y, yb[6] * SA8_Y, yb[7] * SA8_Y)};
.LBB0_567:
	global_load_dwordx4 v[68:71], v[54:55], off
	global_load_dwordx4 v[48:51], v[54:55], off offset:16
	v_lshlrev_b32_e32 v86, 16, v40
	v_mul_f32_e32 v87, 0xbfb8aa3b, v86
	v_and_b32_e32 v73, 0xffff0000, v24
	v_and_b32_e32 v75, 0xffff0000, v32
	v_lshlrev_b32_e32 v63, 16, v25
	v_lshlrev_b32_e32 v77, 16, v33
	v_and_b32_e32 v62, 0xffff0000, v25
	v_and_b32_e32 v76, 0xffff0000, v33
	v_and_b32_e32 v72, 0xffff0000, v28
	v_and_b32_e32 v74, 0xffff0000, v36
	v_lshlrev_b32_e32 v103, 16, v29
	v_lshlrev_b32_e32 v105, 16, v37
	v_and_b32_e32 v102, 0xffff0000, v29
	v_and_b32_e32 v104, 0xffff0000, v37
	v_exp_f32_e32 v87, v87
	v_lshlrev_b32_e32 v59, 16, v24
	v_lshlrev_b32_e32 v61, 16, v32
	v_lshlrev_b32_e32 v79, 16, v26
	v_lshlrev_b32_e32 v81, 16, v34
	v_and_b32_e32 v78, 0xffff0000, v26
	v_and_b32_e32 v80, 0xffff0000, v34
	v_lshlrev_b32_e32 v83, 16, v27
	v_lshlrev_b32_e32 v85, 16, v35
	v_and_b32_e32 v82, 0xffff0000, v27
	v_and_b32_e32 v84, 0xffff0000, v35
	v_lshlrev_b32_e32 v58, 16, v28
	v_lshlrev_b32_e32 v60, 16, v36
	v_lshlrev_b32_e32 v107, 16, v30
	v_lshlrev_b32_e32 v109, 16, v38
	v_and_b32_e32 v106, 0xffff0000, v30
	v_and_b32_e32 v108, 0xffff0000, v38
	v_pk_add_f32 v[76:77], v[76:77], v[62:63]
	v_pk_add_f32 v[62:63], v[104:105], v[102:103]
	v_pk_add_f32 v[72:73], v[74:75], v[72:73]
	v_lshlrev_b32_e32 v111, 16, v31
	v_lshlrev_b32_e32 v113, 16, v39
	v_and_b32_e32 v110, 0xffff0000, v31
	v_and_b32_e32 v112, 0xffff0000, v39
	v_pk_add_f32 v[78:79], v[80:81], v[78:79]
	v_pk_add_f32 v[80:81], v[84:85], v[82:83]
	v_pk_add_f32 v[82:83], v[60:61], v[58:59]
	v_pk_add_f32 v[60:61], v[108:109], v[106:107]
	v_pk_mul_f32 v[74:75], v[76:77], v[76:77]
	v_pk_mul_f32 v[104:105], v[62:63], v[62:63]
	v_pk_mul_f32 v[106:107], v[72:73], v[72:73]
	v_pk_add_f32 v[58:59], v[112:113], v[110:111]
	v_pk_fma_f32 v[106:107], v[82:83], v[82:83], v[106:107]
	v_mov_b32_e32 v112, v105
	v_mov_b32_e32 v113, v75
	v_pk_mul_f32 v[84:85], v[78:79], v[78:79]
	v_pk_mul_f32 v[108:109], v[60:61], v[60:61]
	v_mov_b32_e32 v105, v74
	v_pk_add_f32 v[106:107], v[112:113], v[106:107]
	v_add_f32_e32 v75, 1.0, v87
	v_mov_b32_e32 v74, v109
	v_pk_add_f32 v[104:105], v[104:105], v[106:107]
	v_rcp_f32_e32 v106, v75
	v_mov_b32_e32 v75, v85
	v_pk_mul_f32 v[102:103], v[80:81], v[80:81]
	v_pk_mul_f32 v[110:111], v[58:59], v[58:59]
	v_pk_add_f32 v[74:75], v[74:75], v[104:105]
	v_mov_b32_e32 v109, v84
	v_pk_add_f32 v[74:75], v[108:109], v[74:75]
	v_mov_b32_e32 v84, v111
	v_mov_b32_e32 v85, v103
	v_pk_add_f32 v[74:75], v[84:85], v[74:75]
	v_mov_b32_e32 v111, v102
	v_pk_add_f32 v[74:75], v[110:111], v[74:75]
	v_and_b32_e32 v88, 0xffff0000, v40
	v_lshlrev_b32_e32 v94, 16, v42
	v_mul_f32_e32 v89, 0xbfb8aa3b, v88
	v_mul_f32_e32 v95, 0xbfb8aa3b, v94
	s_waitcnt lgkmcnt(0)
	s_nop 1
	v_add_f32_dpp v74, v74, v74 quad_perm:[1,0,3,2] row_mask:0xf bank_mask:0xf bound_ctrl:1
	v_add_f32_dpp v75, v75, v75 quad_perm:[1,0,3,2] row_mask:0xf bank_mask:0xf bound_ctrl:1
	v_exp_f32_e32 v89, v89
	v_exp_f32_e32 v95, v95
	v_lshlrev_b32_e32 v98, 16, v43
	s_waitcnt vmcnt(1)
	v_mov_b32_e32 v107, v68
	s_waitcnt lgkmcnt(0)
	s_nop 1
	v_add_f32_dpp v74, v74, v74 quad_perm:[2,3,0,1] row_mask:0xf bank_mask:0xf bound_ctrl:1
	v_add_f32_dpp v75, v75, v75 quad_perm:[2,3,0,1] row_mask:0xf bank_mask:0xf bound_ctrl:1
	v_add_f32_e32 v87, 1.0, v89
	v_rcp_f32_e32 v68, v87
	v_add_f32_e32 v87, 1.0, v95
	v_rcp_f32_e32 v102, v87
	s_waitcnt lgkmcnt(0)
	s_nop 1
	v_add_f32_dpp v74, v74, v74 row_half_mirror row_mask:0xf bank_mask:0xf bound_ctrl:1
	v_add_f32_dpp v75, v75, v75 row_half_mirror row_mask:0xf bank_mask:0xf bound_ctrl:1
	v_mul_f32_e32 v87, 0xbfb8aa3b, v98
	s_brev_b32 s2, 60
	v_lshlrev_b32_e32 v90, 16, v41
	v_exp_f32_e32 v87, v87
	s_waitcnt lgkmcnt(0)
	s_nop 1
	v_add_f32_dpp v74, v74, v74 row_mirror row_mask:0xf bank_mask:0xf bound_ctrl:1
	v_add_f32_dpp v75, v75, v75 row_mirror row_mask:0xf bank_mask:0xf bound_ctrl:1
	v_and_b32_e32 v92, 0xffff0000, v41
	v_pk_fma_f32 v[74:75], v[74:75], s[2:3], v[206:207] op_sel_hi:[1,0,0]
	v_mul_f32_e32 v91, 0xbfb8aa3b, v90
	v_mul_f32_e32 v84, 0x4b800000, v75
	v_cmp_gt_f32_e32 vcc, s14, v75
	v_and_b32_e32 v96, 0xffff0000, v42
	v_mul_f32_e32 v93, 0xbfb8aa3b, v92
	v_exp_f32_e32 v91, v91
	v_cndmask_b32_e32 v75, v75, v84, vcc
	v_exp_f32_e32 v93, v93
	s_waitcnt vmcnt(0)
; DI unsigned pk4_fp8(float a, float b, float c, float d) { int w = 0; w = __builtin_amdgcn_cvt_pk_fp8_f32(clamp448(a), clamp448(b), w, false); w = __builtin_amdgcn_cvt_pk_fp8_f32(clamp448(c), clamp448(d), w, true); return (unsigned)w; }
; DI void unpack8(const u32x4 w, float (&f)[8]) { f[0] = bf_lo(w.x); f[1] = bf_hi(w.x); f[2] = bf_lo(w.y); f[3] = bf_hi(w.y); f[4] = bf_lo(w.z); f[5] = bf_hi(w.z); f[6] = bf_lo(w.w); f[7] = bf_hi(w.w); }
; DI float silu(float x) { return x * frcp(1.0f + __expf(-x)); }
; DI void phase_readout(int l, int nrows, int wv) {
;     ...
;             const float rs = rsqrtf(ss * (1.0f / DK) + LN_EPS);
;             unpack8(R.og[c], og);
; #pragma unroll
;             for (int j = 0; j < 8; ++j) yb[j] = o[j] * rs * ng[(e0 + j) & (DK - 1)] * silu(og[j]);
;             *(u32x2*)((unsigned char*)F.H + (size_t)r * D + DC + e0) = (u32x2){pk4_fp8(yb[0] * SA8_Y, yb[1] * SA8_Y, yb[2] * SA8_Y, yb[3] * SA8_Y), pk4_fp8(yb[4] * SA8_Y, yb[5] * SA8_Y, yb[6] * SA8_Y, yb[7] * SA8_Y)};
	v_mov_b32_e32 v103, v48
	v_mul_f32_e32 v48, 0xbfb8aa3b, v96
	v_rsq_f32_e32 v75, v75
	v_and_b32_e32 v100, 0xffff0000, v43
	v_exp_f32_e32 v48, v48
	v_add_f32_e32 v87, 1.0, v87
	v_rcp_f32_e32 v104, v87
	v_mul_f32_e32 v87, 0xbfb8aa3b, v100
	v_add_f32_e32 v89, 1.0, v91
	v_exp_f32_e32 v87, v87
	v_rcp_f32_e32 v112, v89
	v_mov_b32_e32 v113, v70
	v_add_f32_e32 v70, 1.0, v93
	v_mul_f32_e32 v84, 0x45800000, v75
	v_rcp_f32_e32 v70, v70
	v_add_f32_e32 v48, 1.0, v48
	v_cndmask_b32_e32 v75, v75, v84, vcc
	v_rcp_f32_e32 v48, v48
	v_mul_f32_e32 v89, v73, v75
	v_mov_b32_e32 v105, v50
	v_add_f32_e32 v50, 1.0, v87
	v_pk_mul_f32 v[68:69], v[68:69], v[88:89]
	v_mul_f32_e32 v91, v77, v75
	v_rcp_f32_e32 v50, v50
	v_mul_f32_e32 v73, v68, v69
	v_pk_mul_f32 v[68:69], v[112:113], v[90:91]
	v_mul_f32_e32 v93, v76, v75
	v_mul_f32_e32 v77, v68, v69
	v_pk_mul_f32 v[68:69], v[70:71], v[92:93]
	v_mul_f32_e32 v95, v79, v75
	v_mul_f32_e32 v97, v78, v75
	v_mul_f32_e32 v87, v83, v75
	v_mul_f32_e32 v70, v68, v69
	v_pk_mul_f32 v[68:69], v[102:103], v[94:95]
	v_pk_mul_f32 v[48:49], v[48:49], v[96:97]
	v_mul_f32_e32 v99, v81, v75
	v_pk_mul_f32 v[84:85], v[106:107], v[86:87]
	v_mul_f32_e32 v68, v68, v69
	v_mul_f32_e32 v69, v48, v49
	v_pk_mul_f32 v[48:49], v[104:105], v[98:99]
	v_mul_f32_e32 v101, v80, v75
	v_mul_f32_e32 v83, v84, v85
	v_mul_f32_e32 v71, v48, v49
	v_pk_mul_f32 v[48:49], v[50:51], v[100:101]
	v_mul_f32_e32 v51, 0x41000000, v77
	v_mul_f32_e32 v50, v48, v49
	v_mul_f32_e32 v48, 0x41000000, v83
	v_mul_f32_e32 v49, 0x41000000, v73
	v_med3_f32 v73, v48, s33, v238
	v_med3_f32 v49, v49, s33, v238
	v_mov_b32_e32 v48, v129
	v_cvt_pk_fp8_f32 v48, v73, v49
	v_mul_f32_e32 v49, 0x41000000, v70
	v_med3_f32 v51, v51, s33, v238
	v_med3_f32 v49, v49, s33, v238
	v_cvt_pk_fp8_f32 v48, v51, v49 op_sel:[0,0,1]
	v_mul_f32_e32 v49, 0x41000000, v68
	v_mul_f32_e32 v51, 0x41000000, v69
	v_med3_f32 v69, v49, s33, v238
	v_med3_f32 v51, v51, s33, v238
	v_mov_b32_e32 v49, v129
	v_cvt_pk_fp8_f32 v49, v69, v51
	v_mul_f32_e32 v68, 0x41000000, v71
	v_mul_f32_e32 v50, 0x41000000, v50
	v_med3_f32 v51, v68, s33, v238
	v_med3_f32 v50, v50, s33, v238
	v_cvt_pk_fp8_f32 v49, v51, v50 op_sel:[0,0,1]
	s_ashr_i32 s1, s0, 31
	s_lshl_b64 s[2:3], s[0:1], 11
	v_lshl_add_u64 v[76:77], v[56:57], 0, s[2:3]
	global_store_dwordx2 v[76:77], v[48:49], off offset:1024
	global_load_dwordx4 v[48:51], v[54:55], off
	s_nop 0
	global_load_dwordx4 v[68:71], v[54:55], off offset:16
	v_mul_f32_e32 v73, 0x4b800000, v74
	v_cmp_gt_f32_e32 vcc, s14, v74
	v_and_b32_e32 v78, 0xffff0000, v44
	v_mul_f32_e32 v81, 0xbfb8aa3b, v78
	v_cndmask_b32_e32 v73, v74, v73, vcc
	v_rsq_f32_e32 v73, v73
	v_exp_f32_e32 v81, v81
	v_lshlrev_b32_e32 v80, 16, v45
	v_and_b32_e32 v84, 0xffff0000, v45
	v_mul_f32_e32 v74, 0x45800000, v73
	v_cndmask_b32_e32 v73, v73, v74, vcc
	v_lshlrev_b32_e32 v74, 16, v44
	v_mul_f32_e32 v75, 0xbfb8aa3b, v74
	v_exp_f32_e32 v79, v75
	v_mul_f32_e32 v75, v82, v73
	v_mul_f32_e32 v85, v62, v73
	v_lshlrev_b32_e32 v86, 16, v46
	v_add_f32_e32 v79, 1.0, v79
	v_rcp_f32_e32 v82, v79
	v_mul_f32_e32 v79, v72, v73
	v_and_b32_e32 v88, 0xffff0000, v46
	v_mul_f32_e32 v87, v61, v73
	v_mul_f32_e32 v89, v60, v73
	v_lshlrev_b32_e32 v90, 16, v47
	v_and_b32_e32 v92, 0xffff0000, v47
	v_mul_f32_e32 v91, v59, v73
	v_mul_f32_e32 v93, v58, v73
	s_add_i32 s2, s0, s10
	s_cmp_ge_i32 s2, s15
	s_cselect_b64 s[4:5], -1, 0
	s_waitcnt vmcnt(1)
	v_mov_b32_e32 v83, v48
	v_add_f32_e32 v48, 1.0, v81
	v_rcp_f32_e32 v48, v48
	v_mul_f32_e32 v81, v63, v73
	v_pk_mul_f32 v[74:75], v[82:83], v[74:75]
	v_pk_mul_f32 v[48:49], v[48:49], v[78:79]
	s_nop 0
	v_mul_f32_e32 v72, v48, v49
	v_mul_f32_e32 v48, 0xbfb8aa3b, v80
	v_exp_f32_e32 v48, v48
	v_mul_f32_e32 v49, 0xbfb8aa3b, v84
	v_exp_f32_e32 v63, v49
	v_mov_b32_e32 v49, v50
	v_add_f32_e32 v48, 1.0, v48
	v_rcp_f32_e32 v48, v48
	v_add_f32_e32 v50, 1.0, v63
	v_rcp_f32_e32 v50, v50
	v_mul_f32_e32 v74, v74, v75
	v_pk_mul_f32 v[48:49], v[48:49], v[80:81]
	s_nop 0
	v_mul_f32_e32 v63, v48, v49
	v_pk_mul_f32 v[48:49], v[50:51], v[84:85]
	v_mul_f32_e32 v61, 0x41000000, v63
	v_mul_f32_e32 v50, v48, v49
	v_mul_f32_e32 v48, 0xbfb8aa3b, v86
	v_exp_f32_e32 v48, v48
	v_mul_f32_e32 v49, 0xbfb8aa3b, v88
	v_exp_f32_e32 v51, v49
	s_waitcnt vmcnt(0)
	v_mov_b32_e32 v49, v68
	v_add_f32_e32 v48, 1.0, v48
	v_rcp_f32_e32 v48, v48
	v_add_f32_e32 v51, 1.0, v51
	v_rcp_f32_e32 v68, v51
	v_pk_mul_f32 v[48:49], v[48:49], v[86:87]
	s_nop 0
	v_mul_f32_e32 v51, v48, v49
	v_pk_mul_f32 v[48:49], v[68:69], v[88:89]
	s_nop 0
	v_mul_f32_e32 v60, v48, v49
	v_mul_f32_e32 v48, 0xbfb8aa3b, v90
	v_exp_f32_e32 v48, v48
	v_mul_f32_e32 v49, 0xbfb8aa3b, v92
	v_exp_f32_e32 v59, v49
	v_mov_b32_e32 v49, v70
	v_add_f32_e32 v48, 1.0, v48
	v_rcp_f32_e32 v48, v48
	v_add_f32_e32 v59, 1.0, v59
	v_rcp_f32_e32 v70, v59
	v_pk_mul_f32 v[48:49], v[48:49], v[90:91]
	s_nop 0
	v_mul_f32_e32 v59, v48, v49
	v_pk_mul_f32 v[48:49], v[70:71], v[92:93]
	s_nop 0
	v_mul_f32_e32 v58, v48, v49
	v_mul_f32_e32 v48, 0x41000000, v74
	v_mul_f32_e32 v49, 0x41000000, v72
	v_med3_f32 v62, v48, s33, v238
	v_med3_f32 v49, v49, s33, v238
	v_mov_b32_e32 v48, v129
	v_cvt_pk_fp8_f32 v48, v62, v49
	v_mul_f32_e32 v49, 0x41000000, v50
	v_med3_f32 v50, v61, s33, v238
	v_med3_f32 v49, v49, s33, v238
	v_cvt_pk_fp8_f32 v48, v50, v49 op_sel:[0,0,1]
	v_mul_f32_e32 v49, 0x41000000, v51
	v_mul_f32_e32 v50, 0x41000000, v60
	v_mul_f32_e32 v51, 0x41000000, v59
	v_med3_f32 v59, v49, s33, v238
	v_med3_f32 v50, v50, s33, v238
	v_mov_b32_e32 v49, v129
	v_cvt_pk_fp8_f32 v49, v59, v50
	v_mul_f32_e32 v50, 0x41000000, v58
	v_med3_f32 v51, v51, s33, v238
	v_med3_f32 v50, v50, s33, v238
	v_cvt_pk_fp8_f32 v49, v51, v50 op_sel:[0,0,1]
	global_store_dwordx2 v[76:77], v[48:49], off offset:1536

; DI unsigned pk4_fp8(float a, float b, float c, float d) { int w = 0; w = __builtin_amdgcn_cvt_pk_fp8_f32(clamp448(a), clamp448(b), w, false); w = __builtin_amdgcn_cvt_pk_fp8_f32(clamp448(c), clamp448(d), w, true); return (unsigned)w; }
; DI void unpack8(const u32x4 w, float (&f)[8]) { f[0] = bf_lo(w.x); f[1] = bf_hi(w.x); f[2] = bf_lo(w.y); f[3] = bf_hi(w.y); f[4] = bf_lo(w.z); f[5] = bf_hi(w.z); f[6] = bf_lo(w.w); f[7] = bf_hi(w.w); }
; DI float silu(float x) { return x * frcp(1.0f + __expf(-x)); }
; DI void phase_readout(int l, int nrows, int wv) {
;     ...
;     auto row_compute = [&](int r, const RowIn& R) {
; #pragma unroll
;         for (int c = 0; c < 2; ++c) {
;             const int e0 = c * 512 + F.lane * 8;
;             float o[8], og[8], yb[8]; float ss = 0.f;
;             { float fa[8], fb[8]; unpack8(R.a[c], fa); unpack8(R.b[c], fb);
; #pragma unroll
;               for (int j = 0; j < 8; ++j) o[j] = fa[j] + fb[j]; }
; #pragma unroll
;             for (int j = 0; j < 8; ++j) ss += o[j] * o[j];
;             ss += __shfl_xor(ss, 1); ss += __shfl_xor(ss, 2); ss += __shfl_xor(ss, 4); ss += __shfl_xor(ss, 8);
;             const float rs = rsqrtf(ss * (1.0f / DK) + LN_EPS);
;             unpack8(R.og[c], og);
; #pragma unroll
;             for (int j = 0; j < 8; ++j) yb[j] = o[j] * rs * ng[(e0 + j) & (DK - 1)] * silu(og[j]);
;             *(u32x2*)((unsigned char*)F.H + (size_t)r * D + DC + e0) = (u32x2){pk4_fp8(yb[0] * SA8_Y, yb[1] * SA8_Y, yb[2] * SA8_Y, yb[3] * SA8_Y), pk4_fp8(yb[4] * SA8_Y, yb[5] * SA8_Y, yb[6] * SA8_Y, yb[7] * SA8_Y)};
.LBB0_571:
	global_load_dwordx4 v[68:71], v[54:55], off
	global_load_dwordx4 v[48:51], v[54:55], off offset:16
	s_waitcnt vmcnt(3)
	v_lshlrev_b32_e32 v86, 16, v16
	v_mul_f32_e32 v87, 0xbfb8aa3b, v86
	v_and_b32_e32 v73, 0xffff0000, v8
	v_and_b32_e32 v75, 0xffff0000, v0
	v_lshlrev_b32_e32 v63, 16, v9
	v_lshlrev_b32_e32 v77, 16, v1
	v_and_b32_e32 v62, 0xffff0000, v9
	v_and_b32_e32 v76, 0xffff0000, v1
	v_and_b32_e32 v72, 0xffff0000, v12
	v_and_b32_e32 v74, 0xffff0000, v4
	v_lshlrev_b32_e32 v103, 16, v13
	v_lshlrev_b32_e32 v105, 16, v5
	v_and_b32_e32 v102, 0xffff0000, v13
	v_and_b32_e32 v104, 0xffff0000, v5
	v_exp_f32_e32 v87, v87
	v_lshlrev_b32_e32 v59, 16, v8
	v_lshlrev_b32_e32 v61, 16, v0
	v_lshlrev_b32_e32 v79, 16, v10
	v_lshlrev_b32_e32 v81, 16, v2
	v_and_b32_e32 v78, 0xffff0000, v10
	v_and_b32_e32 v80, 0xffff0000, v2
	v_lshlrev_b32_e32 v83, 16, v11
	v_lshlrev_b32_e32 v85, 16, v3
	v_and_b32_e32 v82, 0xffff0000, v11
	v_and_b32_e32 v84, 0xffff0000, v3
	v_lshlrev_b32_e32 v58, 16, v12
	v_lshlrev_b32_e32 v60, 16, v4
	v_lshlrev_b32_e32 v107, 16, v14
	v_lshlrev_b32_e32 v109, 16, v6
	v_and_b32_e32 v106, 0xffff0000, v14
	v_and_b32_e32 v108, 0xffff0000, v6
	v_pk_add_f32 v[76:77], v[76:77], v[62:63]
	v_pk_add_f32 v[62:63], v[104:105], v[102:103]
	v_pk_add_f32 v[72:73], v[74:75], v[72:73]
	v_lshlrev_b32_e32 v111, 16, v15
	v_lshlrev_b32_e32 v113, 16, v7
	v_and_b32_e32 v110, 0xffff0000, v15
	v_and_b32_e32 v112, 0xffff0000, v7
	v_pk_add_f32 v[78:79], v[80:81], v[78:79]
	v_pk_add_f32 v[80:81], v[84:85], v[82:83]
	v_pk_add_f32 v[82:83], v[60:61], v[58:59]
	v_pk_add_f32 v[60:61], v[108:109], v[106:107]
	v_pk_mul_f32 v[74:75], v[76:77], v[76:77]
	v_pk_mul_f32 v[104:105], v[62:63], v[62:63]
	v_pk_mul_f32 v[106:107], v[72:73], v[72:73]
	v_pk_add_f32 v[58:59], v[112:113], v[110:111]
	v_pk_fma_f32 v[106:107], v[82:83], v[82:83], v[106:107]
	v_mov_b32_e32 v112, v105
	v_mov_b32_e32 v113, v75
	v_pk_mul_f32 v[84:85], v[78:79], v[78:79]
	v_pk_mul_f32 v[108:109], v[60:61], v[60:61]
	v_mov_b32_e32 v105, v74
	v_pk_add_f32 v[106:107], v[112:113], v[106:107]
	v_add_f32_e32 v75, 1.0, v87
	v_mov_b32_e32 v74, v109
	v_pk_add_f32 v[104:105], v[104:105], v[106:107]
	v_rcp_f32_e32 v106, v75
	v_mov_b32_e32 v75, v85
	v_pk_mul_f32 v[102:103], v[80:81], v[80:81]
	v_pk_mul_f32 v[110:111], v[58:59], v[58:59]
	v_pk_add_f32 v[74:75], v[74:75], v[104:105]
	v_mov_b32_e32 v109, v84
	v_pk_add_f32 v[74:75], v[108:109], v[74:75]
	v_mov_b32_e32 v84, v111
	v_mov_b32_e32 v85, v103
	v_pk_add_f32 v[74:75], v[84:85], v[74:75]
	v_mov_b32_e32 v111, v102
	v_pk_add_f32 v[74:75], v[110:111], v[74:75]
	v_and_b32_e32 v88, 0xffff0000, v16
	v_lshlrev_b32_e32 v94, 16, v18
	v_mul_f32_e32 v89, 0xbfb8aa3b, v88
	v_mul_f32_e32 v95, 0xbfb8aa3b, v94
	s_waitcnt lgkmcnt(0)
	s_nop 1
	v_add_f32_dpp v74, v74, v74 quad_perm:[1,0,3,2] row_mask:0xf bank_mask:0xf bound_ctrl:1
	v_add_f32_dpp v75, v75, v75 quad_perm:[1,0,3,2] row_mask:0xf bank_mask:0xf bound_ctrl:1
	v_exp_f32_e32 v89, v89
	v_exp_f32_e32 v95, v95
	v_lshlrev_b32_e32 v98, 16, v19
	s_waitcnt vmcnt(1)
	v_mov_b32_e32 v107, v68
	s_waitcnt lgkmcnt(0)
	s_nop 1
	v_add_f32_dpp v74, v74, v74 quad_perm:[2,3,0,1] row_mask:0xf bank_mask:0xf bound_ctrl:1
	v_add_f32_dpp v75, v75, v75 quad_perm:[2,3,0,1] row_mask:0xf bank_mask:0xf bound_ctrl:1
	v_add_f32_e32 v87, 1.0, v89
	v_rcp_f32_e32 v68, v87
	v_add_f32_e32 v87, 1.0, v95
	v_rcp_f32_e32 v102, v87
	s_waitcnt lgkmcnt(0)
	s_nop 1
	v_add_f32_dpp v74, v74, v74 row_half_mirror row_mask:0xf bank_mask:0xf bound_ctrl:1
	v_add_f32_dpp v75, v75, v75 row_half_mirror row_mask:0xf bank_mask:0xf bound_ctrl:1
	v_mul_f32_e32 v87, 0xbfb8aa3b, v98
	s_brev_b32 s12, 60
	v_lshlrev_b32_e32 v90, 16, v17
	v_exp_f32_e32 v87, v87
	s_waitcnt lgkmcnt(0)
	s_nop 1
	v_add_f32_dpp v74, v74, v74 row_mirror row_mask:0xf bank_mask:0xf bound_ctrl:1
	v_add_f32_dpp v75, v75, v75 row_mirror row_mask:0xf bank_mask:0xf bound_ctrl:1
	s_mov_b32 s14, 0x800000
	v_pk_fma_f32 v[74:75], v[74:75], s[12:13], v[206:207] op_sel_hi:[1,0,0]
	v_and_b32_e32 v92, 0xffff0000, v17
	v_mul_f32_e32 v91, 0xbfb8aa3b, v90
	v_mul_f32_e32 v84, 0x4b800000, v75
	v_cmp_gt_f32_e32 vcc, s14, v75
	v_and_b32_e32 v96, 0xffff0000, v18
	v_mul_f32_e32 v93, 0xbfb8aa3b, v92
	v_exp_f32_e32 v91, v91
	v_cndmask_b32_e32 v75, v75, v84, vcc
	v_exp_f32_e32 v93, v93
	s_waitcnt vmcnt(0)
; DI unsigned pk4_fp8(float a, float b, float c, float d) { int w = 0; w = __builtin_amdgcn_cvt_pk_fp8_f32(clamp448(a), clamp448(b), w, false); w = __builtin_amdgcn_cvt_pk_fp8_f32(clamp448(c), clamp448(d), w, true); return (unsigned)w; }
; DI void unpack8(const u32x4 w, float (&f)[8]) { f[0] = bf_lo(w.x); f[1] = bf_hi(w.x); f[2] = bf_lo(w.y); f[3] = bf_hi(w.y); f[4] = bf_lo(w.z); f[5] = bf_hi(w.z); f[6] = bf_lo(w.w); f[7] = bf_hi(w.w); }
; DI float silu(float x) { return x * frcp(1.0f + __expf(-x)); }
; DI void phase_readout(int l, int nrows, int wv) {
;     ...
;             const float rs = rsqrtf(ss * (1.0f / DK) + LN_EPS);
;             unpack8(R.og[c], og);
; #pragma unroll
;             for (int j = 0; j < 8; ++j) yb[j] = o[j] * rs * ng[(e0 + j) & (DK - 1)] * silu(og[j]);
;             *(u32x2*)((unsigned char*)F.H + (size_t)r * D + DC + e0) = (u32x2){pk4_fp8(yb[0] * SA8_Y, yb[1] * SA8_Y, yb[2] * SA8_Y, yb[3] * SA8_Y), pk4_fp8(yb[4] * SA8_Y, yb[5] * SA8_Y, yb[6] * SA8_Y, yb[7] * SA8_Y)};
;         } };
;     RowIn RA, RB;
;     int r = gw;
;     if (r < nrows) row_load(r, RA);
;     while (r < nrows) {
;         const int n1 = r + NGW, n2 = r + 2 * NGW;
;         if (n1 < nrows) row_load(n1, RB);
;         row_compute(r, RA);
;         if (n1 >= nrows) break;
;         if (n2 < nrows) row_load(n2, RA);
;         row_compute(n1, RB);
;         r = n2;
;     }
	v_mov_b32_e32 v103, v48
	v_mul_f32_e32 v48, 0xbfb8aa3b, v96
	v_rsq_f32_e32 v75, v75
	v_and_b32_e32 v100, 0xffff0000, v19
	v_exp_f32_e32 v48, v48
	v_add_f32_e32 v87, 1.0, v87
	v_rcp_f32_e32 v104, v87
	v_mul_f32_e32 v87, 0xbfb8aa3b, v100
	v_add_f32_e32 v89, 1.0, v91
	v_exp_f32_e32 v87, v87
	v_rcp_f32_e32 v112, v89
	v_mov_b32_e32 v113, v70
	v_add_f32_e32 v70, 1.0, v93
	v_mul_f32_e32 v84, 0x45800000, v75
	v_rcp_f32_e32 v70, v70
	v_add_f32_e32 v48, 1.0, v48
	v_cndmask_b32_e32 v75, v75, v84, vcc
	v_rcp_f32_e32 v48, v48
	v_mul_f32_e32 v89, v73, v75
	v_mov_b32_e32 v105, v50
	v_add_f32_e32 v50, 1.0, v87
	v_pk_mul_f32 v[68:69], v[68:69], v[88:89]
	v_mul_f32_e32 v91, v77, v75
	v_rcp_f32_e32 v50, v50
	v_mul_f32_e32 v73, v68, v69
	v_pk_mul_f32 v[68:69], v[112:113], v[90:91]
	v_mul_f32_e32 v93, v76, v75
	v_mul_f32_e32 v77, v68, v69
	v_pk_mul_f32 v[68:69], v[70:71], v[92:93]
	v_mul_f32_e32 v95, v79, v75
	v_mul_f32_e32 v97, v78, v75
	v_mul_f32_e32 v87, v83, v75
	v_mul_f32_e32 v70, v68, v69
	v_pk_mul_f32 v[68:69], v[102:103], v[94:95]
	v_pk_mul_f32 v[48:49], v[48:49], v[96:97]
	v_mul_f32_e32 v99, v81, v75
	v_pk_mul_f32 v[84:85], v[106:107], v[86:87]
	v_mul_f32_e32 v68, v68, v69
	v_mul_f32_e32 v69, v48, v49
	v_pk_mul_f32 v[48:49], v[104:105], v[98:99]
	v_mul_f32_e32 v101, v80, v75
	v_mul_f32_e32 v83, v84, v85
	v_mul_f32_e32 v71, v48, v49
	v_pk_mul_f32 v[48:49], v[50:51], v[100:101]
	v_mul_f32_e32 v51, 0x41000000, v77
	v_mul_f32_e32 v50, v48, v49
	v_mul_f32_e32 v48, 0x41000000, v83
	v_mul_f32_e32 v49, 0x41000000, v73
	v_med3_f32 v73, v48, s33, v238
	v_med3_f32 v49, v49, s33, v238
	v_mov_b32_e32 v48, v129
	v_cvt_pk_fp8_f32 v48, v73, v49
	v_mul_f32_e32 v49, 0x41000000, v70
	v_med3_f32 v51, v51, s33, v238
	v_med3_f32 v49, v49, s33, v238
	v_cvt_pk_fp8_f32 v48, v51, v49 op_sel:[0,0,1]
	v_mul_f32_e32 v49, 0x41000000, v68
	v_mul_f32_e32 v51, 0x41000000, v69
	v_med3_f32 v69, v49, s33, v238
	v_med3_f32 v51, v51, s33, v238
	v_mov_b32_e32 v49, v129
	v_cvt_pk_fp8_f32 v49, v69, v51
	v_mul_f32_e32 v68, 0x41000000, v71
	v_mul_f32_e32 v50, 0x41000000, v50
	v_med3_f32 v51, v68, s33, v238
	v_med3_f32 v50, v50, s33, v238
	v_cvt_pk_fp8_f32 v49, v51, v50 op_sel:[0,0,1]
	s_ashr_i32 s3, s2, 31
	s_lshl_b64 s[12:13], s[2:3], 11
	v_lshl_add_u64 v[76:77], v[56:57], 0, s[12:13]
	global_store_dwordx2 v[76:77], v[48:49], off offset:1024
	global_load_dwordx4 v[48:51], v[54:55], off
	s_nop 0
	global_load_dwordx4 v[68:71], v[54:55], off offset:16
	v_mul_f32_e32 v73, 0x4b800000, v74
	v_cmp_gt_f32_e32 vcc, s14, v74
	v_and_b32_e32 v78, 0xffff0000, v20
	v_mul_f32_e32 v81, 0xbfb8aa3b, v78
	v_cndmask_b32_e32 v73, v74, v73, vcc
	v_rsq_f32_e32 v73, v73
	v_exp_f32_e32 v81, v81
	v_lshlrev_b32_e32 v80, 16, v21
	v_and_b32_e32 v84, 0xffff0000, v21
	v_mul_f32_e32 v74, 0x45800000, v73
	v_cndmask_b32_e32 v73, v73, v74, vcc
	v_lshlrev_b32_e32 v74, 16, v20
	v_mul_f32_e32 v75, 0xbfb8aa3b, v74
	v_exp_f32_e32 v79, v75
	v_mul_f32_e32 v75, v82, v73
	v_mul_f32_e32 v85, v62, v73
	v_lshlrev_b32_e32 v86, 16, v22
	v_add_f32_e32 v79, 1.0, v79
	v_rcp_f32_e32 v82, v79
	v_mul_f32_e32 v79, v72, v73
	v_and_b32_e32 v88, 0xffff0000, v22
	v_mul_f32_e32 v87, v61, v73
	v_mul_f32_e32 v89, v60, v73
	v_lshlrev_b32_e32 v90, 16, v23
	v_and_b32_e32 v92, 0xffff0000, v23
	v_mul_f32_e32 v91, v59, v73
	v_mul_f32_e32 v93, v58, v73
	s_andn2_b64 vcc, exec, s[4:5]
	s_mov_b64 s[4:5], -1
	s_waitcnt vmcnt(1)
	v_mov_b32_e32 v83, v48
	v_add_f32_e32 v48, 1.0, v81
	v_rcp_f32_e32 v48, v48
	v_mul_f32_e32 v81, v63, v73
	v_pk_mul_f32 v[74:75], v[82:83], v[74:75]
	v_pk_mul_f32 v[48:49], v[48:49], v[78:79]
	s_nop 0
	v_mul_f32_e32 v72, v48, v49
	v_mul_f32_e32 v48, 0xbfb8aa3b, v80
	v_exp_f32_e32 v48, v48
	v_mul_f32_e32 v49, 0xbfb8aa3b, v84
	v_exp_f32_e32 v63, v49
	v_mov_b32_e32 v49, v50
	v_add_f32_e32 v48, 1.0, v48
	v_rcp_f32_e32 v48, v48
	v_add_f32_e32 v50, 1.0, v63
	v_rcp_f32_e32 v50, v50
	v_mul_f32_e32 v74, v74, v75
	v_pk_mul_f32 v[48:49], v[48:49], v[80:81]
	s_nop 0
	v_mul_f32_e32 v63, v48, v49
	v_pk_mul_f32 v[48:49], v[50:51], v[84:85]
	v_mul_f32_e32 v61, 0x41000000, v63
	v_mul_f32_e32 v50, v48, v49
	v_mul_f32_e32 v48, 0xbfb8aa3b, v86
	v_exp_f32_e32 v48, v48
	v_mul_f32_e32 v49, 0xbfb8aa3b, v88
	v_exp_f32_e32 v51, v49
	s_waitcnt vmcnt(0)
	v_mov_b32_e32 v49, v68
	v_add_f32_e32 v48, 1.0, v48
	v_rcp_f32_e32 v48, v48
	v_add_f32_e32 v51, 1.0, v51
	v_rcp_f32_e32 v68, v51
	v_pk_mul_f32 v[48:49], v[48:49], v[86:87]
	s_nop 0
	v_mul_f32_e32 v51, v48, v49
	v_pk_mul_f32 v[48:49], v[68:69], v[88:89]
	s_nop 0
	v_mul_f32_e32 v60, v48, v49
	v_mul_f32_e32 v48, 0xbfb8aa3b, v90
	v_exp_f32_e32 v48, v48
	v_mul_f32_e32 v49, 0xbfb8aa3b, v92
	v_exp_f32_e32 v59, v49
	v_mov_b32_e32 v49, v70
	v_add_f32_e32 v48, 1.0, v48
	v_rcp_f32_e32 v48, v48
	v_add_f32_e32 v59, 1.0, v59
	v_rcp_f32_e32 v70, v59
	v_pk_mul_f32 v[48:49], v[48:49], v[90:91]
	s_nop 0
	v_mul_f32_e32 v59, v48, v49
	v_pk_mul_f32 v[48:49], v[70:71], v[92:93]
	s_nop 0
	v_mul_f32_e32 v58, v48, v49
	v_mul_f32_e32 v48, 0x41000000, v74
	v_mul_f32_e32 v49, 0x41000000, v72
	v_med3_f32 v62, v48, s33, v238
	v_med3_f32 v49, v49, s33, v238
	v_mov_b32_e32 v48, v129
	v_cvt_pk_fp8_f32 v48, v62, v49
	v_mul_f32_e32 v49, 0x41000000, v50
	v_med3_f32 v50, v61, s33, v238
	v_med3_f32 v49, v49, s33, v238
	v_cvt_pk_fp8_f32 v48, v50, v49 op_sel:[0,0,1]
	v_mul_f32_e32 v49, 0x41000000, v51
	v_mul_f32_e32 v50, 0x41000000, v60
	v_mul_f32_e32 v51, 0x41000000, v59
	v_med3_f32 v59, v49, s33, v238
	v_med3_f32 v50, v50, s33, v238
	v_mov_b32_e32 v49, v129
	v_cvt_pk_fp8_f32 v49, v59, v50
	v_mul_f32_e32 v50, 0x41000000, v58
	v_med3_f32 v51, v51, s33, v238
	v_med3_f32 v50, v50, s33, v238
	v_cvt_pk_fp8_f32 v49, v51, v50 op_sel:[0,0,1]
	global_store_dwordx2 v[76:77], v[48:49], off offset:1536
	s_cbranch_vccnz .LBB0_568
	s_add_i32 s2, s11, s2
	s_cmp_ge_i32 s2, s15
	s_cbranch_scc1 .LBB0_567
	s_ashr_i32 s3, s2, 31
	s_mul_i32 s4, s2, 0x6000
	s_mul_hi_i32 s1, s2, 0x6000
	s_add_u32 s4, s6, s4
	s_addc_u32 s5, s7, s1
	s_lshl_b64 s[2:3], s[2:3], 11
	s_add_u32 s2, s8, s2
	s_addc_u32 s3, s9, s3
	v_lshl_add_u64 v[4:5], s[2:3], 0, v[52:53]
	v_add_co_u32_e32 v8, vcc, 0x2400000, v4
	s_mov_b64 s[2:3], 0x2400000
	s_nop 0
	v_addc_co_u32_e32 v9, vcc, 0, v5, vcc
	v_lshl_add_u64 v[0:1], s[4:5], 0, v[52:53]
	v_lshl_add_u64 v[12:13], v[4:5], 0, s[2:3]
	s_mov_b64 s[2:3], 0x3800
	v_add_co_u32_e32 v16, vcc, 0x3000, v0
	v_lshl_add_u64 v[20:21], v[0:1], 0, s[2:3]
	s_nop 0
	v_addc_co_u32_e32 v17, vcc, 0, v1, vcc
	global_load_dwordx4 v[0:3], v[4:5], off
	s_nop 0
	global_load_dwordx4 v[4:7], v[4:5], off offset:1024
	s_nop 0
	global_load_dwordx4 v[8:11], v[8:9], off
	s_nop 0
	global_load_dwordx4 v[12:15], v[12:13], off offset:1024
	s_nop 0
	global_load_dwordx4 v[16:19], v[16:17], off offset:2048
	s_nop 0
	global_load_dwordx4 v[20:23], v[20:21], off offset:1024
	s_branch .LBB0_567
